# static s_setprio 1 for the LEADING wave half (waves 0-3) set once at kernel entry; per-phase priority flips removed from the four GEMM K-loops
# speedup vs baseline: 1.0089x; 1.0022x over previous
; #define LAS __attribute__((address_space(3)))
; __global__ void __launch_bounds__(NTHR, 2) hybrid_fwd(Args args) {
;     ...
;     const bool t0 = (wave == 0) && (__builtin_amdgcn_mbcnt_hi(~0u, __builtin_amdgcn_mbcnt_lo(~0u, 0u)) == 0);
;     if (args.ph_lo < 0) grid.sync();
;     volatile LAS unsigned* bst = (volatile LAS unsigned*)(lds + RING_BYTES);
;     if (t0) { bst[0] = 0u; bst[1] = 0u; }
;     __syncthreads();
;     XcdBarrier xbar = xcd_barrier_post(ctl + 1024, bst, t0);
.LBB0_7:
	s_or_b64 exec, exec, s[4:5]
	s_lshr_b32 s74, s3, 6
	s_cmp_lt_u32 s74, 4
	s_cbranch_scc0 .Lhy_prio_skip
	s_setprio 1
